# memattn_block q load: the 32 split-K partial loads issued as two bursts of 16 (first one behind the row-scale loads) instead of 8 x (4 loads -> vmcnt(0))
# speedup vs baseline: 1.0204x; 1.0070x over previous
; DI float bf2f(bf16_t v) { return __uint_as_float(((unsigned)v) << 16); }
; DI void memattn_block(const Params& p, int layer, int bh, int tile4) {
;     ...
;   for (int kt = 0; kt < 8; ++kt) kv_issue(ldsb + kt * AT_STAGE, Kb + (size_t)kt * 4096, VT + (size_t)kt * 4096, L);
;   bf16x8 qf[8];
;   if (wid < 4) {
;     const size_t mrow = (size_t)b * T_ + tq;
;     const bf16_t* qp = (const bf16_t*)(p.ws + A_SCR) + mrow * 512 + h * 128 + g * 8;
;     const float* sp8 = (const float*)(p.ws + A_SSP) + SZ_SSP / 4 + mrow * 8;
;     const f32x4 s0 = *(const f32x4*)sp8, s1 = *(const f32x4*)(sp8 + 4);
;     const float rr = rsqrtf((((s0[0] + s0[1]) + (s0[2] + s0[3])) + ((s1[0] + s1[1]) + (s1[2] + s1[3]))) * (1.f / D_) + EPS_);
;     f32x4 qa[8], qb[8]; float ss = 0.f;
; #pragma unroll
;     for (int ks = 0; ks < 8; ++ks) {
;       f32x4 a = (f32x4){0.f, 0.f, 0.f, 0.f}, c = a;
; #pragma unroll
;       for (int sp = 0; sp < 4; ++sp) { const bf16x8 r8 = *(const bf16x8*)(qp + (size_t)sp * M_ * 512 + ks * 16);
; #pragma unroll
;         for (int i = 0; i < 4; ++i) { a[i] += bf2f((bf16_t)r8[i]); c[i] += bf2f((bf16_t)r8[4 + i]); } }
;       a = a * rr; c = c * rr; qa[ks] = a; qb[ks] = c;
.LBB0_104:
	v_mov_b32_e32 v116, v199
	s_ashr_i32 s14, s20, 5
	v_readfirstlane_b32 s12, v116
	s_ashr_i32 s13, s12, 6
	s_lshl_b32 s12, s20, 7
	s_and_b32 s21, s12, 0xf80
	s_lshl_b32 s12, s13, 5
	s_ashr_i32 s15, s14, 31
	s_and_b32 s26, s12, 0x60
	s_ashr_i32 s12, s20, 7
	s_lshl_b64 s[22:23], s[14:15], 16
	s_add_u32 s15, s22, s0
	s_addc_u32 s25, s23, s1
	s_add_u32 s22, s16, s15
	v_ashrrev_i32_e32 v0, 4, v116
	s_addc_u32 s23, s17, s25
	v_lshlrev_b32_e32 v2, 8, v0
	v_xor_b32_e32 v0, v0, v116
	s_add_u32 s24, s18, s15
	v_lshlrev_b32_e32 v0, 4, v0
	s_movk_i32 s15, 0xf0
	s_addc_u32 s25, s19, s25
	v_and_or_b32 v0, v0, s15, v2
	s_lshl_b32 s15, s13, 10
	s_add_i32 s15, s15, 0
	s_mov_b32 m0, s15
	v_lshlrev_b32_e32 v18, 4, v116
	s_waitcnt lgkmcnt(0)
	v_lshl_add_u64 v[2:3], s[22:23], 0, v[0:1]
	v_mov_b32_e32 v19, v1
	global_load_lds_dwordx4 v0, s[22:23]
	s_add_i32 m0, s15, 0x2000
	s_mov_b64 s[22:23], 0x2000
	v_lshl_add_u64 v[4:5], s[24:25], 0, v[18:19]
	global_load_lds_dwordx4 v18, s[24:25]
	v_lshl_add_u64 v[6:7], v[2:3], 0, s[22:23]
	s_add_i32 m0, s15, 0x4000
	v_and_b32_e32 v19, 31, v116
	global_load_lds_dwordx4 v[6:7], off
	v_lshl_add_u64 v[6:7], v[4:5], 0, s[22:23]
	s_add_i32 m0, s15, 0x6000
	s_mov_b64 s[22:23], 0x4000
	global_load_lds_dwordx4 v[6:7], off
	v_lshl_add_u64 v[6:7], v[2:3], 0, s[22:23]
	s_add_i32 m0, s15, 0x8000
	v_bfe_u32 v114, v116, 5, 1
	global_load_lds_dwordx4 v[6:7], off
	v_lshl_add_u64 v[6:7], v[4:5], 0, s[22:23]
	s_add_i32 m0, s15, 0xa000
	s_mov_b64 s[22:23], 0x6000
	global_load_lds_dwordx4 v[6:7], off
	v_lshl_add_u64 v[6:7], v[2:3], 0, s[22:23]
	s_add_i32 m0, s15, 0xc000
	s_nop 0
	global_load_lds_dwordx4 v[6:7], off
	v_lshl_add_u64 v[6:7], v[4:5], 0, s[22:23]
	s_add_i32 m0, s15, 0xe000
	s_mov_b64 s[22:23], 0x8000
	global_load_lds_dwordx4 v[6:7], off
	v_lshl_add_u64 v[6:7], v[2:3], 0, s[22:23]
	s_add_i32 m0, s15, 0x10000
	s_nop 0
	global_load_lds_dwordx4 v[6:7], off
	v_lshl_add_u64 v[6:7], v[4:5], 0, s[22:23]
	s_add_i32 m0, s15, 0x12000
	s_mov_b64 s[22:23], 0xa000
	global_load_lds_dwordx4 v[6:7], off
	v_lshl_add_u64 v[6:7], v[2:3], 0, s[22:23]
	s_add_i32 m0, s15, 0x14000
	s_nop 0
	global_load_lds_dwordx4 v[6:7], off
	v_lshl_add_u64 v[6:7], v[4:5], 0, s[22:23]
	s_add_i32 m0, s15, 0x16000
	s_mov_b64 s[22:23], 0xc000
	global_load_lds_dwordx4 v[6:7], off
	v_lshl_add_u64 v[6:7], v[2:3], 0, s[22:23]
	s_add_i32 m0, s15, 0x18000
	s_nop 0
	global_load_lds_dwordx4 v[6:7], off
	v_lshl_add_u64 v[6:7], v[4:5], 0, s[22:23]
	s_add_i32 m0, s15, 0x1a000
	s_mov_b64 s[22:23], 0xe000
	global_load_lds_dwordx4 v[6:7], off
	v_lshl_add_u64 v[2:3], v[2:3], 0, s[22:23]
	s_add_i32 m0, s15, 0x1c000
	s_nop 0
	global_load_lds_dwordx4 v[2:3], off
	v_lshl_add_u64 v[2:3], v[4:5], 0, s[22:23]
	s_add_i32 m0, s15, 0x1e000
	s_or_b32 s22, s21, s26
	global_load_lds_dwordx4 v[2:3], off
	s_and_b32 s21, s14, 3
	s_cmp_lt_i32 s13, 4
	s_cselect_b64 s[14:15], -1, 0
	s_cmp_gt_i32 s13, 3
	v_or_b32_e32 v115, s22, v19
	s_cbranch_scc1 .LBB0_106
	s_ashr_i32 s13, s12, 31
	s_lshl_b64 s[22:23], s[12:13], 12
	v_or_b32_e32 v2, s22, v115
	v_mov_b32_e32 v3, s23
	v_lshlrev_b64 v[4:5], 10, v[2:3]
	v_readlane_b32 s22, v253, 10
	v_lshl_add_u64 v[4:5], s[4:5], 0, v[4:5]
	v_readlane_b32 s23, v253, 11
	s_lshl_b32 s22, s21, 8
	v_lshlrev_b32_e32 v6, 4, v114
	v_lshl_add_u64 v[4:5], v[4:5], 0, s[22:23]
	v_mov_b32_e32 v7, v1
	v_lshlrev_b64 v[2:3], 5, v[2:3]
	v_lshl_add_u64 v[36:37], v[4:5], 0, v[6:7]
	s_mov_b64 s[100:101], 0x800000
	v_lshl_add_u64 v[42:43], v[36:37], 0, s[100:101]
	s_mov_b64 s[100:101], 0x1000000
	v_lshl_add_u64 v[40:41], v[36:37], 0, s[100:101]
	s_mov_b64 s[100:101], 0x1800000
	v_lshl_add_u64 v[38:39], v[36:37], 0, s[100:101]
	v_lshl_add_u64 v[6:7], s[6:7], 0, v[2:3]
	global_load_dwordx4 v[2:5], v[6:7], off
	s_nop 0
	global_load_dwordx4 v[6:9], v[6:7], off offset:16
	global_load_dwordx4 v[200:203], v[36:37], off
	global_load_dwordx4 v[204:207], v[42:43], off
	global_load_dwordx4 v[208:211], v[40:41], off
	global_load_dwordx4 v[212:215], v[38:39], off
	global_load_dwordx4 v[216:219], v[36:37], off offset:32
	global_load_dwordx4 v[220:223], v[42:43], off offset:32
	global_load_dwordx4 v[224:227], v[40:41], off offset:32
	global_load_dwordx4 v[228:231], v[38:39], off offset:32
	global_load_dwordx4 v[232:235], v[36:37], off offset:64
	global_load_dwordx4 v[236:239], v[42:43], off offset:64
	global_load_dwordx4 v[240:243], v[40:41], off offset:64
	global_load_dwordx4 v[244:247], v[38:39], off offset:64
	global_load_dwordx4 v[148:151], v[36:37], off offset:96
	global_load_dwordx4 v[152:155], v[42:43], off offset:96
	global_load_dwordx4 v[156:159], v[40:41], off offset:96
	global_load_dwordx4 v[160:163], v[38:39], off offset:96
	s_mov_b32 s22, 0x800000
	s_mov_b32 s13, s23
	v_writelane_b32 v253, s12, 10
	s_mov_b32 s84, 0x800000
	s_waitcnt vmcnt(16)
	v_mov_b32_e32 v10, v2
	v_mov_b32_e32 v11, v6
	v_mov_b32_e32 v6, v3
	v_pk_add_f32 v[2:3], v[10:11], v[6:7]
	v_mov_b32_e32 v6, v4
	v_mov_b32_e32 v7, v8
	v_mov_b32_e32 v8, v5
	v_pk_add_f32 v[4:5], v[6:7], v[8:9]
	v_writelane_b32 v253, s13, 11
	v_pk_add_f32 v[2:3], v[2:3], v[4:5]
	s_mov_b32 s13, 0x1000000
	v_add_f32_e32 v0, v2, v3
	v_fmamk_f32 v0, v0, 0x3a000000, v249
	v_cmp_gt_f32_e32 vcc, s22, v0
	v_mul_f32_e32 v2, 0x4b800000, v0
	s_nop 0
	v_cndmask_b32_e32 v0, v0, v2, vcc
	v_rsq_f32_e32 v0, v0
	s_nop 0
	v_mul_f32_e32 v2, 0x45800000, v0
	v_cndmask_b32_e32 v0, v0, v2, vcc
	s_nop 0
	s_mov_b32 s13, 0x1800000
	s_nop 0
	s_waitcnt vmcnt(13)
; DI float bf2f(bf16_t v) { return __uint_as_float(((unsigned)v) << 16); }
; DI void memattn_block(const Params& p, int layer, int bh, int tile4) {
;     ...
;     for (int ks = 0; ks < 8; ++ks) {
;       f32x4 a = (f32x4){0.f, 0.f, 0.f, 0.f}, c = a;
; #pragma unroll
;       for (int sp = 0; sp < 4; ++sp) { const bf16x8 r8 = *(const bf16x8*)(qp + (size_t)sp * M_ * 512 + ks * 16);
; #pragma unroll
;         for (int i = 0; i < 4; ++i) { a[i] += bf2f((bf16_t)r8[i]); c[i] += bf2f((bf16_t)r8[4 + i]); } }
;       a = a * rr; c = c * rr; qa[ks] = a; qb[ks] = c;
;       ss += (a[0] * a[0] + a[1] * a[1]) + (a[2] * a[2] + a[3] * a[3]) + (c[0] * c[0] + c[1] * c[1]) + (c[2] * c[2] + c[3] * c[3]);
	v_and_b32_e32 v23, 0xffff0000, v204
	v_and_b32_e32 v21, 0xffff0000, v200
	v_lshlrev_b32_e32 v20, 16, v200
	v_pk_add_f32 v[20:21], v[20:21], 0 op_sel_hi:[1,0]
	v_lshlrev_b32_e32 v22, 16, v204
	v_pk_add_f32 v[20:21], v[20:21], v[22:23]
	v_and_b32_e32 v23, 0xffff0000, v208
	v_lshlrev_b32_e32 v22, 16, v208
	v_pk_add_f32 v[20:21], v[20:21], v[22:23]
	v_and_b32_e32 v25, 0xffff0000, v206
	v_lshlrev_b32_e32 v24, 16, v206
	v_lshlrev_b32_e32 v6, 16, v209
	s_waitcnt vmcnt(12)
	v_and_b32_e32 v23, 0xffff0000, v212
	v_lshlrev_b32_e32 v22, 16, v212
	v_pk_add_f32 v[22:23], v[20:21], v[22:23]
	v_and_b32_e32 v21, 0xffff0000, v202
	v_lshlrev_b32_e32 v20, 16, v202
	v_pk_add_f32 v[20:21], v[20:21], 0 op_sel_hi:[1,0]
	s_nop 0
	v_pk_add_f32 v[20:21], v[20:21], v[24:25]
	v_and_b32_e32 v25, 0xffff0000, v210
	v_lshlrev_b32_e32 v24, 16, v210
	v_pk_add_f32 v[20:21], v[20:21], v[24:25]
	v_and_b32_e32 v25, 0xffff0000, v214
	v_lshlrev_b32_e32 v24, 16, v214
	v_pk_add_f32 v[26:27], v[20:21], v[24:25]
	v_and_b32_e32 v21, 0xffff0000, v201
	v_lshlrev_b32_e32 v20, 16, v201
	v_pk_add_f32 v[2:3], v[20:21], 0 op_sel_hi:[1,0]
	v_and_b32_e32 v21, 0xffff0000, v205
	v_lshlrev_b32_e32 v20, 16, v205
	v_pk_add_f32 v[2:3], v[2:3], v[20:21]
	v_and_b32_e32 v7, 0xffff0000, v209
	v_pk_add_f32 v[2:3], v[2:3], v[6:7]
	v_and_b32_e32 v7, 0xffff0000, v213
	v_lshlrev_b32_e32 v6, 16, v213
	v_pk_add_f32 v[2:3], v[2:3], v[6:7]
	v_and_b32_e32 v7, 0xffff0000, v203
	v_lshlrev_b32_e32 v6, 16, v203
	v_pk_add_f32 v[4:5], v[6:7], 0 op_sel_hi:[1,0]
	v_and_b32_e32 v7, 0xffff0000, v207
	v_lshlrev_b32_e32 v6, 16, v207
	v_pk_add_f32 v[4:5], v[4:5], v[6:7]
	v_and_b32_e32 v7, 0xffff0000, v211
	v_lshlrev_b32_e32 v6, 16, v211
	v_pk_add_f32 v[4:5], v[4:5], v[6:7]
	v_and_b32_e32 v7, 0xffff0000, v215
	v_lshlrev_b32_e32 v6, 16, v215
	v_pk_add_f32 v[4:5], v[4:5], v[6:7]
	v_pk_mul_f32 v[20:21], v[0:1], v[2:3] op_sel_hi:[0,1]
	v_pk_mul_f32 v[24:25], v[0:1], v[22:23] op_sel_hi:[0,1]
	v_pk_mul_f32 v[22:23], v[0:1], v[4:5] op_sel_hi:[0,1]
	v_pk_mul_f32 v[26:27], v[0:1], v[26:27] op_sel_hi:[0,1]
	s_waitcnt vmcnt(8)
	v_and_b32_e32 v29, 0xffff0000, v216
	v_lshlrev_b32_e32 v28, 16, v216
	v_pk_add_f32 v[28:29], v[28:29], 0 op_sel_hi:[1,0]
	v_and_b32_e32 v31, 0xffff0000, v220
	v_lshlrev_b32_e32 v30, 16, v220
	v_pk_add_f32 v[28:29], v[28:29], v[30:31]
	v_and_b32_e32 v31, 0xffff0000, v224
	v_lshlrev_b32_e32 v30, 16, v224
	v_pk_add_f32 v[28:29], v[28:29], v[30:31]
	v_and_b32_e32 v31, 0xffff0000, v228
	v_lshlrev_b32_e32 v30, 16, v228
	v_pk_add_f32 v[30:31], v[28:29], v[30:31]
	v_and_b32_e32 v29, 0xffff0000, v218
	v_lshlrev_b32_e32 v28, 16, v218
	v_pk_add_f32 v[28:29], v[28:29], 0 op_sel_hi:[1,0]
	v_and_b32_e32 v33, 0xffff0000, v222
	v_lshlrev_b32_e32 v32, 16, v222
	v_pk_add_f32 v[28:29], v[28:29], v[32:33]
	v_and_b32_e32 v33, 0xffff0000, v226
	v_lshlrev_b32_e32 v32, 16, v226
	v_pk_add_f32 v[28:29], v[28:29], v[32:33]
	v_and_b32_e32 v33, 0xffff0000, v230
	v_lshlrev_b32_e32 v32, 16, v230
	v_pk_add_f32 v[34:35], v[28:29], v[32:33]
	v_and_b32_e32 v29, 0xffff0000, v217
	v_lshlrev_b32_e32 v28, 16, v217
	v_pk_add_f32 v[14:15], v[28:29], 0 op_sel_hi:[1,0]
	v_and_b32_e32 v29, 0xffff0000, v221
	v_lshlrev_b32_e32 v28, 16, v221
	v_pk_add_f32 v[10:11], v[14:15], v[28:29]
	v_and_b32_e32 v15, 0xffff0000, v225
	v_lshlrev_b32_e32 v14, 16, v225
	v_pk_add_f32 v[6:7], v[10:11], v[14:15]
	v_and_b32_e32 v11, 0xffff0000, v229
	v_lshlrev_b32_e32 v10, 16, v229
	v_pk_add_f32 v[2:3], v[6:7], v[10:11]
	v_and_b32_e32 v7, 0xffff0000, v219
	v_lshlrev_b32_e32 v6, 16, v219
	v_pk_add_f32 v[6:7], v[6:7], 0 op_sel_hi:[1,0]
	v_and_b32_e32 v11, 0xffff0000, v223
	v_lshlrev_b32_e32 v10, 16, v223
	v_pk_add_f32 v[6:7], v[6:7], v[10:11]
	v_and_b32_e32 v11, 0xffff0000, v227
	v_lshlrev_b32_e32 v10, 16, v227
	v_pk_add_f32 v[6:7], v[6:7], v[10:11]
	v_and_b32_e32 v9, 0xffff0000, v231
	v_lshlrev_b32_e32 v8, 16, v231
	v_pk_add_f32 v[4:5], v[6:7], v[8:9]
	v_pk_mul_f32 v[32:33], v[0:1], v[30:31] op_sel_hi:[0,1]
	v_pk_mul_f32 v[28:29], v[0:1], v[2:3] op_sel_hi:[0,1]
	v_pk_mul_f32 v[30:31], v[0:1], v[4:5] op_sel_hi:[0,1]
	v_mov_b32_e32 v4, v25
	v_mov_b32_e32 v5, v33
	v_mov_b32_e32 v2, v24
	v_mov_b32_e32 v3, v32
	v_pk_mul_f32 v[4:5], v[4:5], v[4:5]
	v_mov_b32_e32 v6, v21
	v_mov_b32_e32 v7, v29
	v_pk_mul_f32 v[34:35], v[0:1], v[34:35] op_sel_hi:[0,1]
	v_pk_fma_f32 v[2:3], v[2:3], v[2:3], v[4:5]
	v_mov_b32_e32 v4, v20
	v_mov_b32_e32 v5, v28
	v_pk_mul_f32 v[6:7], v[6:7], v[6:7]
	s_nop 0
	v_pk_fma_f32 v[4:5], v[4:5], v[4:5], v[6:7]
	v_mov_b32_e32 v6, v27
	v_mov_b32_e32 v7, v35
	v_pk_add_f32 v[2:3], v[2:3], v[4:5]
	v_mov_b32_e32 v4, v26
	v_mov_b32_e32 v5, v34
	v_pk_mul_f32 v[6:7], v[6:7], v[6:7]
	s_nop 0
	v_pk_fma_f32 v[4:5], v[4:5], v[4:5], v[6:7]
	v_mov_b32_e32 v6, v23
	v_mov_b32_e32 v7, v31
	v_pk_add_f32 v[2:3], v[4:5], v[2:3]
	v_mov_b32_e32 v4, v22
	v_mov_b32_e32 v5, v30
	v_pk_mul_f32 v[6:7], v[6:7], v[6:7]
	s_nop 0
	v_pk_fma_f32 v[4:5], v[4:5], v[4:5], v[6:7]
	s_nop 0
	v_pk_add_f32 v[2:3], v[4:5], v[2:3]
	v_pk_add_f32 v[2:3], v[2:3], v[2:3] op_sel:[0,1] op_sel_hi:[1,0]
	s_waitcnt vmcnt(4)
; DI float bf2f(bf16_t v) { return __uint_as_float(((unsigned)v) << 16); }
; DI void memattn_block(const Params& p, int layer, int bh, int tile4) {
;     ...
;     for (int ks = 0; ks < 8; ++ks) {
;       f32x4 a = (f32x4){0.f, 0.f, 0.f, 0.f}, c = a;
; #pragma unroll
;       for (int sp = 0; sp < 4; ++sp) { const bf16x8 r8 = *(const bf16x8*)(qp + (size_t)sp * M_ * 512 + ks * 16);
; #pragma unroll
;         for (int i = 0; i < 4; ++i) { a[i] += bf2f((bf16_t)r8[i]); c[i] += bf2f((bf16_t)r8[4 + i]); } }
;       a = a * rr; c = c * rr; qa[ks] = a; qb[ks] = c;
;       ss += (a[0] * a[0] + a[1] * a[1]) + (a[2] * a[2] + a[3] * a[3]) + (c[0] * c[0] + c[1] * c[1]) + (c[2] * c[2] + c[3] * c[3]);
	v_and_b32_e32 v17, 0xffff0000, v232
	v_lshlrev_b32_e32 v16, 16, v232
	v_pk_add_f32 v[16:17], v[16:17], 0 op_sel_hi:[1,0]
	v_and_b32_e32 v49, 0xffff0000, v236
	v_lshlrev_b32_e32 v48, 16, v236
	v_pk_add_f32 v[16:17], v[16:17], v[48:49]
	v_and_b32_e32 v49, 0xffff0000, v240
	v_lshlrev_b32_e32 v48, 16, v240
	v_pk_add_f32 v[16:17], v[16:17], v[48:49]
	v_and_b32_e32 v49, 0xffff0000, v244
	v_lshlrev_b32_e32 v48, 16, v244
	v_pk_add_f32 v[16:17], v[16:17], v[48:49]
	v_and_b32_e32 v49, 0xffff0000, v234
	v_lshlrev_b32_e32 v48, 16, v234
	v_pk_add_f32 v[48:49], v[48:49], 0 op_sel_hi:[1,0]
	v_and_b32_e32 v51, 0xffff0000, v238
	v_lshlrev_b32_e32 v50, 16, v238
	v_pk_add_f32 v[48:49], v[48:49], v[50:51]
	v_and_b32_e32 v51, 0xffff0000, v242
	v_lshlrev_b32_e32 v50, 16, v242
	v_pk_add_f32 v[48:49], v[48:49], v[50:51]
	v_and_b32_e32 v51, 0xffff0000, v246
	v_lshlrev_b32_e32 v50, 16, v246
	v_pk_add_f32 v[50:51], v[48:49], v[50:51]
	v_and_b32_e32 v49, 0xffff0000, v233
	v_lshlrev_b32_e32 v48, 16, v233
	v_pk_add_f32 v[4:5], v[48:49], 0 op_sel_hi:[1,0]
	v_and_b32_e32 v49, 0xffff0000, v237
	v_lshlrev_b32_e32 v48, 16, v237
	v_pk_add_f32 v[4:5], v[4:5], v[48:49]
	v_and_b32_e32 v9, 0xffff0000, v241
	v_lshlrev_b32_e32 v8, 16, v241
	v_pk_add_f32 v[4:5], v[4:5], v[8:9]
	v_and_b32_e32 v9, 0xffff0000, v245
	v_lshlrev_b32_e32 v8, 16, v245
	v_pk_add_f32 v[4:5], v[4:5], v[8:9]
	v_and_b32_e32 v9, 0xffff0000, v235
	v_lshlrev_b32_e32 v8, 16, v235
	v_pk_add_f32 v[6:7], v[8:9], 0 op_sel_hi:[1,0]
	v_and_b32_e32 v9, 0xffff0000, v239
	v_lshlrev_b32_e32 v8, 16, v239
	v_pk_add_f32 v[6:7], v[6:7], v[8:9]
	v_and_b32_e32 v9, 0xffff0000, v243
	v_lshlrev_b32_e32 v8, 16, v243
	v_pk_add_f32 v[6:7], v[6:7], v[8:9]
	v_and_b32_e32 v9, 0xffff0000, v247
	v_lshlrev_b32_e32 v8, 16, v247
	v_pk_add_f32 v[6:7], v[6:7], v[8:9]
	v_pk_mul_f32 v[48:49], v[0:1], v[16:17] op_sel_hi:[0,1]
	v_pk_mul_f32 v[44:45], v[0:1], v[4:5] op_sel_hi:[0,1]
	v_pk_mul_f32 v[46:47], v[0:1], v[6:7] op_sel_hi:[0,1]
	v_pk_mul_f32 v[4:5], v[44:45], v[44:45]
	v_pk_mul_f32 v[6:7], v[48:49], v[48:49]
	v_pk_mul_f32 v[50:51], v[0:1], v[50:51] op_sel_hi:[0,1]
	v_pk_mov_b32 v[8:9], v[6:7], v[4:5] op_sel:[1,0]
	v_mov_b32_e32 v7, v5
	v_pk_add_f32 v[4:5], v[8:9], v[6:7]
	v_pk_mul_f32 v[6:7], v[46:47], v[46:47]
	v_pk_mul_f32 v[8:9], v[50:51], v[50:51]
	v_mov_b32_e32 v10, v6
	v_mov_b32_e32 v11, v8
	v_mov_b32_e32 v8, v7
	v_pk_add_f32 v[4:5], v[4:5], v[4:5] op_sel:[0,1] op_sel_hi:[1,0]
	v_pk_add_f32 v[6:7], v[10:11], v[8:9]
	s_nop 0
	v_pk_add_f32 v[4:5], v[6:7], v[4:5] op_sel:[1,0] op_sel_hi:[0,1]
	v_pk_add_f32 v[4:5], v[6:7], v[4:5]
	s_waitcnt vmcnt(0)
	v_and_b32_e32 v57, 0xffff0000, v148
	v_lshlrev_b32_e32 v56, 16, v148
	v_pk_add_f32 v[56:57], v[56:57], 0 op_sel_hi:[1,0]
	v_and_b32_e32 v59, 0xffff0000, v152
	v_lshlrev_b32_e32 v58, 16, v152
	v_pk_add_f32 v[56:57], v[56:57], v[58:59]
	v_and_b32_e32 v59, 0xffff0000, v156
	v_lshlrev_b32_e32 v58, 16, v156
	v_pk_add_f32 v[56:57], v[56:57], v[58:59]
	v_and_b32_e32 v59, 0xffff0000, v160
	v_lshlrev_b32_e32 v58, 16, v160
	v_pk_add_f32 v[56:57], v[56:57], v[58:59]
	v_and_b32_e32 v59, 0xffff0000, v150
	v_lshlrev_b32_e32 v58, 16, v150
	v_pk_add_f32 v[58:59], v[58:59], 0 op_sel_hi:[1,0]
	v_and_b32_e32 v61, 0xffff0000, v154
	v_lshlrev_b32_e32 v60, 16, v154
	v_pk_add_f32 v[58:59], v[58:59], v[60:61]
	v_and_b32_e32 v61, 0xffff0000, v158
	v_lshlrev_b32_e32 v60, 16, v158
	v_pk_add_f32 v[58:59], v[58:59], v[60:61]
	v_and_b32_e32 v61, 0xffff0000, v162
	v_lshlrev_b32_e32 v60, 16, v162
	v_pk_add_f32 v[58:59], v[58:59], v[60:61]
	v_and_b32_e32 v61, 0xffff0000, v149
	v_lshlrev_b32_e32 v60, 16, v149
	v_pk_add_f32 v[6:7], v[60:61], 0 op_sel_hi:[1,0]
	v_and_b32_e32 v61, 0xffff0000, v153
	v_lshlrev_b32_e32 v60, 16, v153
	v_pk_add_f32 v[6:7], v[6:7], v[60:61]
	v_and_b32_e32 v11, 0xffff0000, v157
	v_lshlrev_b32_e32 v10, 16, v157
	v_pk_add_f32 v[6:7], v[6:7], v[10:11]
	v_and_b32_e32 v11, 0xffff0000, v161
	v_lshlrev_b32_e32 v10, 16, v161
	v_pk_add_f32 v[6:7], v[6:7], v[10:11]
	v_and_b32_e32 v11, 0xffff0000, v151
	v_lshlrev_b32_e32 v10, 16, v151
	v_pk_add_f32 v[8:9], v[10:11], 0 op_sel_hi:[1,0]
	v_and_b32_e32 v11, 0xffff0000, v155
	v_lshlrev_b32_e32 v10, 16, v155
	v_pk_add_f32 v[8:9], v[8:9], v[10:11]
	v_and_b32_e32 v11, 0xffff0000, v159
	v_lshlrev_b32_e32 v10, 16, v159
	v_pk_add_f32 v[8:9], v[8:9], v[10:11]
	v_and_b32_e32 v11, 0xffff0000, v163
	v_lshlrev_b32_e32 v10, 16, v163
	v_pk_add_f32 v[8:9], v[8:9], v[10:11]
	v_pk_mul_f32 v[52:53], v[0:1], v[6:7] op_sel_hi:[0,1]
	v_pk_mul_f32 v[54:55], v[0:1], v[8:9] op_sel_hi:[0,1]
	global_load_dwordx4 v[164:167], v[36:37], off offset:128
	global_load_dwordx4 v[168:171], v[42:43], off offset:128
	global_load_dwordx4 v[172:175], v[40:41], off offset:128
	global_load_dwordx4 v[176:179], v[38:39], off offset:128
	global_load_dwordx4 v[180:183], v[36:37], off offset:160
	global_load_dwordx4 v[184:187], v[42:43], off offset:160
	global_load_dwordx4 v[188:191], v[40:41], off offset:160
	global_load_dwordx4 v[200:203], v[38:39], off offset:160
	global_load_dwordx4 v[204:207], v[36:37], off offset:192
	global_load_dwordx4 v[208:211], v[42:43], off offset:192
	global_load_dwordx4 v[212:215], v[40:41], off offset:192
	global_load_dwordx4 v[216:219], v[38:39], off offset:192
	global_load_dwordx4 v[220:223], v[36:37], off offset:224
	global_load_dwordx4 v[224:227], v[42:43], off offset:224
	global_load_dwordx4 v[228:231], v[40:41], off offset:224
	global_load_dwordx4 v[232:235], v[38:39], off offset:224
	v_pk_mul_f32 v[58:59], v[0:1], v[58:59] op_sel_hi:[0,1]
	v_pk_mul_f32 v[56:57], v[0:1], v[56:57] op_sel_hi:[0,1]
	s_waitcnt vmcnt(12)
; DI float bf2f(bf16_t v) { return __uint_as_float(((unsigned)v) << 16); }
; DI void memattn_block(const Params& p, int layer, int bh, int tile4) {
;     ...
;     for (int ks = 0; ks < 8; ++ks) {
;       f32x4 a = (f32x4){0.f, 0.f, 0.f, 0.f}, c = a;
; #pragma unroll
;       for (int sp = 0; sp < 4; ++sp) { const bf16x8 r8 = *(const bf16x8*)(qp + (size_t)sp * M_ * 512 + ks * 16);
; #pragma unroll
;         for (int i = 0; i < 4; ++i) { a[i] += bf2f((bf16_t)r8[i]); c[i] += bf2f((bf16_t)r8[4 + i]); } }
;       a = a * rr; c = c * rr; qa[ks] = a; qb[ks] = c;
;       ss += (a[0] * a[0] + a[1] * a[1]) + (a[2] * a[2] + a[3] * a[3]) + (c[0] * c[0] + c[1] * c[1]) + (c[2] * c[2] + c[3] * c[3]);
	v_and_b32_e32 v65, 0xffff0000, v164
	v_lshlrev_b32_e32 v64, 16, v164
	v_pk_add_f32 v[64:65], v[64:65], 0 op_sel_hi:[1,0]
	v_and_b32_e32 v67, 0xffff0000, v168
	v_lshlrev_b32_e32 v66, 16, v168
	v_pk_add_f32 v[64:65], v[64:65], v[66:67]
	v_and_b32_e32 v67, 0xffff0000, v172
	v_lshlrev_b32_e32 v66, 16, v172
	v_pk_add_f32 v[64:65], v[64:65], v[66:67]
	v_and_b32_e32 v67, 0xffff0000, v176
	v_lshlrev_b32_e32 v66, 16, v176
	v_pk_add_f32 v[64:65], v[64:65], v[66:67]
	v_and_b32_e32 v67, 0xffff0000, v166
	v_lshlrev_b32_e32 v66, 16, v166
	v_pk_add_f32 v[66:67], v[66:67], 0 op_sel_hi:[1,0]
	v_and_b32_e32 v69, 0xffff0000, v170
	v_lshlrev_b32_e32 v68, 16, v170
	v_pk_add_f32 v[66:67], v[66:67], v[68:69]
	v_and_b32_e32 v69, 0xffff0000, v174
	v_lshlrev_b32_e32 v68, 16, v174
	v_pk_add_f32 v[66:67], v[66:67], v[68:69]
	v_and_b32_e32 v69, 0xffff0000, v178
	v_lshlrev_b32_e32 v68, 16, v178
	v_pk_add_f32 v[66:67], v[66:67], v[68:69]
	v_and_b32_e32 v69, 0xffff0000, v165
	v_lshlrev_b32_e32 v68, 16, v165
	v_pk_add_f32 v[6:7], v[68:69], 0 op_sel_hi:[1,0]
	v_and_b32_e32 v69, 0xffff0000, v169
	v_lshlrev_b32_e32 v68, 16, v169
	v_pk_add_f32 v[6:7], v[6:7], v[68:69]
	v_and_b32_e32 v11, 0xffff0000, v173
	v_lshlrev_b32_e32 v10, 16, v173
	v_pk_add_f32 v[6:7], v[6:7], v[10:11]
	v_and_b32_e32 v11, 0xffff0000, v177
	v_lshlrev_b32_e32 v10, 16, v177
	v_pk_add_f32 v[6:7], v[6:7], v[10:11]
	v_and_b32_e32 v11, 0xffff0000, v167
	v_lshlrev_b32_e32 v10, 16, v167
	v_pk_add_f32 v[8:9], v[10:11], 0 op_sel_hi:[1,0]
	v_and_b32_e32 v11, 0xffff0000, v171
	v_lshlrev_b32_e32 v10, 16, v171
	v_pk_add_f32 v[8:9], v[8:9], v[10:11]
	v_and_b32_e32 v11, 0xffff0000, v175
	v_lshlrev_b32_e32 v10, 16, v175
	v_pk_add_f32 v[8:9], v[8:9], v[10:11]
	v_and_b32_e32 v11, 0xffff0000, v179
	v_lshlrev_b32_e32 v10, 16, v179
	v_pk_add_f32 v[8:9], v[8:9], v[10:11]
	v_pk_mul_f32 v[64:65], v[0:1], v[64:65] op_sel_hi:[0,1]
	v_pk_mul_f32 v[62:63], v[0:1], v[8:9] op_sel_hi:[0,1]
	v_mov_b32_e32 v8, v59
	v_mov_b32_e32 v9, v65
	v_pk_mul_f32 v[60:61], v[0:1], v[6:7] op_sel_hi:[0,1]
	v_mov_b32_e32 v6, v58
	v_mov_b32_e32 v7, v64
	v_pk_mul_f32 v[8:9], v[8:9], v[8:9]
	v_mul_f32_e32 v10, v60, v60
	v_pk_fma_f32 v[6:7], v[6:7], v[6:7], v[8:9]
	v_mul_f32_e32 v8, v57, v57
	v_pk_fma_f32 v[8:9], v[56:57], v[56:57], v[8:9] op_sel_hi:[1,1,0]
	v_mul_f32_e32 v12, v61, v61
	v_mov_b32_e32 v9, v10
	v_mul_f32_e32 v10, v53, v53
	v_pk_fma_f32 v[10:11], v[52:53], v[52:53], v[10:11] op_sel_hi:[1,1,0]
	v_pk_mul_f32 v[66:67], v[0:1], v[66:67] op_sel_hi:[0,1]
	v_mov_b32_e32 v11, v12
	v_pk_add_f32 v[8:9], v[8:9], v[10:11]
	v_mov_b32_e32 v10, v55
	v_mov_b32_e32 v11, v67
	v_mul_f32_e32 v13, v62, v62
	v_pk_add_f32 v[6:7], v[6:7], v[8:9]
	v_mov_b32_e32 v8, v54
	v_mov_b32_e32 v9, v66
	v_pk_mul_f32 v[10:11], v[10:11], v[10:11]
	v_mul_f32_e32 v5, v63, v63
	v_pk_fma_f32 v[8:9], v[8:9], v[8:9], v[10:11]
	v_mov_b32_e32 v3, v13
	v_pk_add_f32 v[6:7], v[8:9], v[6:7]
	v_pk_add_f32 v[2:3], v[2:3], v[4:5]
	s_nop 0
	v_pk_add_f32 v[76:77], v[2:3], v[6:7]
	s_waitcnt vmcnt(8)
	v_and_b32_e32 v69, 0xffff0000, v180
	v_lshlrev_b32_e32 v68, 16, v180
	v_pk_add_f32 v[68:69], v[68:69], 0 op_sel_hi:[1,0]
	v_and_b32_e32 v71, 0xffff0000, v184
	v_lshlrev_b32_e32 v70, 16, v184
	v_pk_add_f32 v[68:69], v[68:69], v[70:71]
	v_and_b32_e32 v71, 0xffff0000, v188
	v_lshlrev_b32_e32 v70, 16, v188
	v_pk_add_f32 v[68:69], v[68:69], v[70:71]
	v_and_b32_e32 v71, 0xffff0000, v200
	v_lshlrev_b32_e32 v70, 16, v200
	v_pk_add_f32 v[68:69], v[68:69], v[70:71]
	v_and_b32_e32 v71, 0xffff0000, v182
	v_lshlrev_b32_e32 v70, 16, v182
	v_pk_add_f32 v[70:71], v[70:71], 0 op_sel_hi:[1,0]
	v_and_b32_e32 v73, 0xffff0000, v186
	v_lshlrev_b32_e32 v72, 16, v186
	v_pk_add_f32 v[70:71], v[70:71], v[72:73]
	v_and_b32_e32 v73, 0xffff0000, v190
	v_lshlrev_b32_e32 v72, 16, v190
	v_pk_add_f32 v[70:71], v[70:71], v[72:73]
	v_and_b32_e32 v73, 0xffff0000, v202
	v_lshlrev_b32_e32 v72, 16, v202
	v_pk_add_f32 v[70:71], v[70:71], v[72:73]
	v_and_b32_e32 v73, 0xffff0000, v181
	v_lshlrev_b32_e32 v72, 16, v181
	v_pk_add_f32 v[2:3], v[72:73], 0 op_sel_hi:[1,0]
	v_and_b32_e32 v73, 0xffff0000, v185
	v_lshlrev_b32_e32 v72, 16, v185
	v_pk_add_f32 v[2:3], v[2:3], v[72:73]
	v_and_b32_e32 v7, 0xffff0000, v189
	v_lshlrev_b32_e32 v6, 16, v189
	v_pk_add_f32 v[2:3], v[2:3], v[6:7]
	v_and_b32_e32 v7, 0xffff0000, v201
	v_lshlrev_b32_e32 v6, 16, v201
	v_pk_add_f32 v[2:3], v[2:3], v[6:7]
	v_and_b32_e32 v7, 0xffff0000, v183
	v_lshlrev_b32_e32 v6, 16, v183
	v_pk_add_f32 v[4:5], v[6:7], 0 op_sel_hi:[1,0]
	v_and_b32_e32 v7, 0xffff0000, v187
	v_lshlrev_b32_e32 v6, 16, v187
	v_pk_add_f32 v[4:5], v[4:5], v[6:7]
	v_and_b32_e32 v7, 0xffff0000, v191
	v_lshlrev_b32_e32 v6, 16, v191
	v_pk_add_f32 v[4:5], v[4:5], v[6:7]
	v_and_b32_e32 v7, 0xffff0000, v203
	v_lshlrev_b32_e32 v6, 16, v203
	v_pk_add_f32 v[4:5], v[4:5], v[6:7]
	v_pk_mul_f32 v[72:73], v[0:1], v[68:69] op_sel_hi:[0,1]
	v_pk_mul_f32 v[68:69], v[0:1], v[2:3] op_sel_hi:[0,1]
	v_pk_mul_f32 v[74:75], v[0:1], v[70:71] op_sel_hi:[0,1]
	v_pk_mul_f32 v[70:71], v[0:1], v[4:5] op_sel_hi:[0,1]
	v_pk_mul_f32 v[2:3], v[68:69], v[68:69]
	v_pk_mul_f32 v[4:5], v[72:73], v[72:73]
	s_nop 0
	v_pk_mov_b32 v[6:7], v[4:5], v[2:3] op_sel:[1,0]
	v_mov_b32_e32 v5, v3
	v_pk_add_f32 v[2:3], v[6:7], v[4:5]
	v_pk_mul_f32 v[4:5], v[70:71], v[70:71]
	v_pk_mul_f32 v[6:7], v[74:75], v[74:75]
	v_mov_b32_e32 v8, v4
	v_mov_b32_e32 v9, v6
	v_mov_b32_e32 v6, v5
	v_pk_add_f32 v[2:3], v[2:3], v[2:3] op_sel:[0,1] op_sel_hi:[1,0]
	v_pk_add_f32 v[4:5], v[8:9], v[6:7]
	s_nop 0
	v_pk_add_f32 v[2:3], v[4:5], v[2:3] op_sel:[1,0] op_sel_hi:[0,1]
	v_pk_add_f32 v[82:83], v[4:5], v[2:3]
	s_waitcnt vmcnt(4)
; DI float bf2f(bf16_t v) { return __uint_as_float(((unsigned)v) << 16); }
; DI float xhalf_sum(float v) { const auto r = __builtin_amdgcn_permlane32_swap(__float_as_uint(v), __float_as_uint(v), false, false); return __uint_as_float(r[0]) + __uint_as_float(r[1]); }
; DI void memattn_block(const Params& p, int layer, int bh, int tile4) {
;     ...
;     for (int ks = 0; ks < 8; ++ks) {
;       f32x4 a = (f32x4){0.f, 0.f, 0.f, 0.f}, c = a;
; #pragma unroll
;       for (int sp = 0; sp < 4; ++sp) { const bf16x8 r8 = *(const bf16x8*)(qp + (size_t)sp * M_ * 512 + ks * 16);
; #pragma unroll
;         for (int i = 0; i < 4; ++i) { a[i] += bf2f((bf16_t)r8[i]); c[i] += bf2f((bf16_t)r8[4 + i]); } }
;       a = a * rr; c = c * rr; qa[ks] = a; qb[ks] = c;
;       ss += (a[0] * a[0] + a[1] * a[1]) + (a[2] * a[2] + a[3] * a[3]) + (c[0] * c[0] + c[1] * c[1]) + (c[2] * c[2] + c[3] * c[3]);
;     }
;     ss = xhalf_sum(ss);
;     const float rs = rsqrtf(ss * (1.f / 128.f) + EPS_) * (ATTN_SCALE * LOG2E);
;     const float* gain = p.in[26] + layer * 128 + g * 8;
; #pragma unroll
;     for (int ks = 0; ks < 8; ++ks) {
;       const f32x4 g0 = *(const f32x4*)(gain + ks * 16), g1 = *(const f32x4*)(gain + ks * 16 + 4);
	v_and_b32_e32 v79, 0xffff0000, v204
	v_lshlrev_b32_e32 v78, 16, v204
	v_pk_add_f32 v[78:79], v[78:79], 0 op_sel_hi:[1,0]
	v_and_b32_e32 v81, 0xffff0000, v208
	v_lshlrev_b32_e32 v80, 16, v208
	v_pk_add_f32 v[78:79], v[78:79], v[80:81]
	v_and_b32_e32 v81, 0xffff0000, v212
	v_lshlrev_b32_e32 v80, 16, v212
	v_pk_add_f32 v[78:79], v[78:79], v[80:81]
	v_and_b32_e32 v81, 0xffff0000, v216
	v_lshlrev_b32_e32 v80, 16, v216
	v_pk_add_f32 v[80:81], v[78:79], v[80:81]
	v_and_b32_e32 v79, 0xffff0000, v206
	v_lshlrev_b32_e32 v78, 16, v206
	v_pk_add_f32 v[78:79], v[78:79], 0 op_sel_hi:[1,0]
	v_and_b32_e32 v85, 0xffff0000, v210
	v_lshlrev_b32_e32 v84, 16, v210
	v_pk_add_f32 v[78:79], v[78:79], v[84:85]
	v_and_b32_e32 v85, 0xffff0000, v214
	v_lshlrev_b32_e32 v84, 16, v214
	v_pk_add_f32 v[78:79], v[78:79], v[84:85]
	v_and_b32_e32 v85, 0xffff0000, v218
	v_lshlrev_b32_e32 v84, 16, v218
	v_pk_add_f32 v[84:85], v[78:79], v[84:85]
	v_and_b32_e32 v79, 0xffff0000, v205
	v_lshlrev_b32_e32 v78, 16, v205
	v_pk_add_f32 v[2:3], v[78:79], 0 op_sel_hi:[1,0]
	v_and_b32_e32 v79, 0xffff0000, v209
	v_lshlrev_b32_e32 v78, 16, v209
	v_pk_add_f32 v[2:3], v[2:3], v[78:79]
	v_and_b32_e32 v7, 0xffff0000, v213
	v_lshlrev_b32_e32 v6, 16, v213
	v_pk_add_f32 v[2:3], v[2:3], v[6:7]
	v_and_b32_e32 v7, 0xffff0000, v217
	v_lshlrev_b32_e32 v6, 16, v217
	v_pk_add_f32 v[2:3], v[2:3], v[6:7]
	v_and_b32_e32 v7, 0xffff0000, v207
	v_lshlrev_b32_e32 v6, 16, v207
	v_pk_add_f32 v[4:5], v[6:7], 0 op_sel_hi:[1,0]
	v_and_b32_e32 v7, 0xffff0000, v211
	v_lshlrev_b32_e32 v6, 16, v211
	v_pk_add_f32 v[4:5], v[4:5], v[6:7]
	v_and_b32_e32 v7, 0xffff0000, v215
	v_lshlrev_b32_e32 v6, 16, v215
	v_pk_add_f32 v[4:5], v[4:5], v[6:7]
	v_and_b32_e32 v7, 0xffff0000, v219
	v_lshlrev_b32_e32 v6, 16, v219
	v_pk_add_f32 v[4:5], v[4:5], v[6:7]
	v_pk_mul_f32 v[78:79], v[0:1], v[2:3] op_sel_hi:[0,1]
	v_pk_mul_f32 v[106:107], v[0:1], v[80:81] op_sel_hi:[0,1]
	v_pk_mul_f32 v[80:81], v[0:1], v[4:5] op_sel_hi:[0,1]
	v_pk_mul_f32 v[108:109], v[0:1], v[84:85] op_sel_hi:[0,1]
	s_waitcnt vmcnt(0)
	v_and_b32_e32 v37, 0xffff0000, v220
	v_lshlrev_b32_e32 v36, 16, v220
	v_pk_add_f32 v[36:37], v[36:37], 0 op_sel_hi:[1,0]
	v_and_b32_e32 v39, 0xffff0000, v224
	v_lshlrev_b32_e32 v38, 16, v224
	v_pk_add_f32 v[36:37], v[36:37], v[38:39]
	v_and_b32_e32 v39, 0xffff0000, v228
	v_lshlrev_b32_e32 v38, 16, v228
	v_pk_add_f32 v[36:37], v[36:37], v[38:39]
	v_and_b32_e32 v39, 0xffff0000, v232
	v_lshlrev_b32_e32 v38, 16, v232
	v_pk_add_f32 v[36:37], v[36:37], v[38:39]
	v_and_b32_e32 v39, 0xffff0000, v222
	v_lshlrev_b32_e32 v38, 16, v222
	v_pk_add_f32 v[38:39], v[38:39], 0 op_sel_hi:[1,0]
	v_and_b32_e32 v41, 0xffff0000, v226
	v_lshlrev_b32_e32 v40, 16, v226
	v_pk_add_f32 v[38:39], v[38:39], v[40:41]
	v_and_b32_e32 v41, 0xffff0000, v230
	v_lshlrev_b32_e32 v40, 16, v230
	v_pk_add_f32 v[38:39], v[38:39], v[40:41]
	v_and_b32_e32 v41, 0xffff0000, v234
	v_lshlrev_b32_e32 v40, 16, v234
	v_pk_add_f32 v[38:39], v[38:39], v[40:41]
	v_and_b32_e32 v41, 0xffff0000, v221
	v_lshlrev_b32_e32 v40, 16, v221
	v_pk_add_f32 v[2:3], v[40:41], 0 op_sel_hi:[1,0]
	v_and_b32_e32 v41, 0xffff0000, v225
	v_lshlrev_b32_e32 v40, 16, v225
	v_pk_add_f32 v[2:3], v[2:3], v[40:41]
	v_and_b32_e32 v7, 0xffff0000, v229
	v_lshlrev_b32_e32 v6, 16, v229
	v_pk_add_f32 v[2:3], v[2:3], v[6:7]
	v_and_b32_e32 v7, 0xffff0000, v233
	v_lshlrev_b32_e32 v6, 16, v233
	v_pk_add_f32 v[2:3], v[2:3], v[6:7]
	v_and_b32_e32 v7, 0xffff0000, v223
	v_lshlrev_b32_e32 v6, 16, v223
	v_pk_add_f32 v[4:5], v[6:7], 0 op_sel_hi:[1,0]
	v_and_b32_e32 v7, 0xffff0000, v227
	v_lshlrev_b32_e32 v6, 16, v227
	v_pk_add_f32 v[4:5], v[4:5], v[6:7]
	v_and_b32_e32 v7, 0xffff0000, v231
	v_lshlrev_b32_e32 v6, 16, v231
	v_pk_add_f32 v[4:5], v[4:5], v[6:7]
	v_and_b32_e32 v7, 0xffff0000, v235
	v_lshlrev_b32_e32 v6, 16, v235
	v_pk_add_f32 v[4:5], v[4:5], v[6:7]
	v_pk_mul_f32 v[14:15], v[0:1], v[36:37] op_sel_hi:[0,1]
	v_pk_mul_f32 v[10:11], v[0:1], v[4:5] op_sel_hi:[0,1]
	v_mov_b32_e32 v4, v109
	v_mov_b32_e32 v5, v15
	v_pk_mul_f32 v[12:13], v[0:1], v[2:3] op_sel_hi:[0,1]
	v_pk_mul_f32 v[16:17], v[0:1], v[38:39] op_sel_hi:[0,1]
	v_mov_b32_e32 v2, v108
	v_mov_b32_e32 v3, v14
	v_pk_mul_f32 v[4:5], v[4:5], v[4:5]
	v_mul_f32_e32 v0, v107, v107
	v_mul_f32_e32 v6, v12, v12
	v_pk_fma_f32 v[2:3], v[2:3], v[2:3], v[4:5]
	v_pk_fma_f32 v[4:5], v[106:107], v[106:107], v[0:1] op_sel_hi:[1,1,0]
	v_mul_f32_e32 v0, v79, v79
	v_mul_f32_e32 v8, v13, v13
	v_mov_b32_e32 v5, v6
	v_pk_fma_f32 v[6:7], v[78:79], v[78:79], v[0:1] op_sel_hi:[1,1,0]
	v_mul_f32_e32 v9, v10, v10
	v_mov_b32_e32 v7, v8
	v_pk_add_f32 v[4:5], v[4:5], v[6:7]
	v_mov_b32_e32 v6, v81
	v_mov_b32_e32 v7, v17
	v_pk_add_f32 v[2:3], v[2:3], v[4:5]
	v_mov_b32_e32 v4, v80
	v_mov_b32_e32 v5, v16
	v_pk_mul_f32 v[6:7], v[6:7], v[6:7]
	v_mul_f32_e32 v83, v11, v11
	v_pk_fma_f32 v[4:5], v[4:5], v[4:5], v[6:7]
	v_lshlrev_b32_e32 v6, 5, v114
	v_pk_add_f32 v[2:3], v[4:5], v[2:3]
	v_pk_add_f32 v[4:5], v[76:77], v[76:77] op_sel:[0,1] op_sel_hi:[1,0]
	s_nop 0
	v_mov_b32_e32 v5, v9
	v_pk_add_f32 v[4:5], v[4:5], v[82:83]
	s_nop 0
	v_pk_add_f32 v[2:3], v[4:5], v[2:3]
	s_nop 0
	v_pk_add_f32 v[2:3], v[2:3], v[2:3] op_sel:[0,1] op_sel_hi:[1,0]
	s_nop 0
	v_mov_b32_e32 v0, v2
	s_nop 1
	v_permlane32_swap_b32_e32 v2, v0
	v_add_f32_e32 v0, v2, v0
	v_fmamk_f32 v0, v0, 0x3c000000, v249
	v_cmp_gt_f32_e32 vcc, s22, v0
	v_mul_f32_e32 v2, 0x4b800000, v0
	s_nop 0
	v_cndmask_b32_e32 v0, v0, v2, vcc
	v_rsq_f32_e32 v0, v0
	s_nop 0
	v_mul_f32_e32 v2, 0x45800000, v0
	v_cndmask_b32_e32 v0, v0, v2, vcc
	global_load_dwordx4 v[200:203], v6, s[8:9] offset:16
	global_load_dwordx4 v[204:207], v6, s[8:9]
	global_load_dwordx4 v[208:211], v6, s[8:9] offset:80
	global_load_dwordx4 v[212:215], v6, s[8:9] offset:64
	global_load_dwordx4 v[216:219], v6, s[8:9] offset:144
	global_load_dwordx4 v[220:223], v6, s[8:9] offset:128
	global_load_dwordx4 v[224:227], v6, s[8:9] offset:208
	global_load_dwordx4 v[228:231], v6, s[8:9] offset:192
	global_load_dwordx4 v[232:235], v6, s[8:9] offset:272
	global_load_dwordx4 v[236:239], v6, s[8:9] offset:256
	global_load_dwordx4 v[240:243], v6, s[8:9] offset:336
	global_load_dwordx4 v[244:247], v6, s[8:9] offset:320
	global_load_dwordx4 v[156:159], v6, s[8:9] offset:400
	global_load_dwordx4 v[160:163], v6, s[8:9] offset:384
	global_load_dwordx4 v[164:167], v6, s[8:9] offset:464
	global_load_dwordx4 v[168:171], v6, s[8:9] offset:448
	v_mul_f32_e32 v0, 0x3e0293ee, v0
	v_pk_mul_f32 v[8:9], v[24:25], v[0:1] op_sel_hi:[1,0]
	v_pk_mul_f32 v[24:25], v[26:27], v[0:1] op_sel_hi:[1,0]
	v_pk_mul_f32 v[20:21], v[20:21], v[0:1] op_sel_hi:[1,0]
	v_pk_mul_f32 v[22:23], v[22:23], v[0:1] op_sel_hi:[1,0]
	v_pk_mul_f32 v[14:15], v[14:15], v[0:1] op_sel_hi:[1,0]
	v_pk_mul_f32 v[12:13], v[12:13], v[0:1] op_sel_hi:[1,0]
	v_pk_mul_f32 v[10:11], v[10:11], v[0:1] op_sel_hi:[1,0]
	s_waitcnt vmcnt(14)
; DI bf16x8 pack8(const float* p) { u32x4 o; o.x = pk2h(p[0], p[1]); o.y = pk2h(p[2], p[3]); o.z = pk2h(p[4], p[5]); o.w = pk2h(p[6], p[7]); return __builtin_bit_cast(bf16x8, o); }
; DI void memattn_block(const Params& p, int layer, int bh, int tile4) {
;     ...
; #pragma unroll
;     for (int ks = 0; ks < 8; ++ks) {
;       const f32x4 g0 = *(const f32x4*)(gain + ks * 16), g1 = *(const f32x4*)(gain + ks * 16 + 4);
;       float v[8];
; #pragma unroll
;       for (int i = 0; i < 4; ++i) { v[i] = qa[ks][i] * rs * g0[i]; v[4 + i] = qb[ks][i] * rs * g1[i]; }
;       qf[ks] = pack8(v);
;     }
	v_pk_mul_f32 v[2:3], v[200:201], v[24:25]
	v_pk_mul_f32 v[20:21], v[206:207], v[20:21]
	v_pk_mul_f32 v[4:5], v[202:203], v[22:23]
	v_cvt_pk_bf16_f32 v83, v20, v21
	v_cvt_pk_bf16_f32 v84, v2, v3
	v_cvt_pk_bf16_f32 v85, v4, v5
	v_pk_mul_f32 v[8:9], v[204:205], v[8:9]
	s_nop 0
	v_cvt_pk_bf16_f32 v82, v8, v9
	v_pk_mul_f32 v[8:9], v[32:33], v[0:1] op_sel_hi:[1,0]
	s_waitcnt vmcnt(12)
	v_pk_mul_f32 v[8:9], v[212:213], v[8:9]
	v_pk_mul_f32 v[20:21], v[34:35], v[0:1] op_sel_hi:[1,0]
	v_cvt_pk_bf16_f32 v86, v8, v9
	v_pk_mul_f32 v[2:3], v[208:209], v[20:21]
	v_pk_mul_f32 v[20:21], v[28:29], v[0:1] op_sel_hi:[1,0]
	v_cvt_pk_bf16_f32 v88, v2, v3
	v_pk_mul_f32 v[20:21], v[214:215], v[20:21]
	v_pk_mul_f32 v[22:23], v[30:31], v[0:1] op_sel_hi:[1,0]
	v_cvt_pk_bf16_f32 v87, v20, v21
	v_pk_mul_f32 v[4:5], v[210:211], v[22:23]
	v_pk_mul_f32 v[8:9], v[48:49], v[0:1] op_sel_hi:[1,0]
	v_cvt_pk_bf16_f32 v89, v4, v5
	s_waitcnt vmcnt(10)
	v_pk_mul_f32 v[8:9], v[220:221], v[8:9]
	v_pk_mul_f32 v[20:21], v[50:51], v[0:1] op_sel_hi:[1,0]
	v_cvt_pk_bf16_f32 v90, v8, v9
	v_pk_mul_f32 v[2:3], v[216:217], v[20:21]
	v_pk_mul_f32 v[20:21], v[44:45], v[0:1] op_sel_hi:[1,0]
	v_cvt_pk_bf16_f32 v92, v2, v3
	v_pk_mul_f32 v[20:21], v[222:223], v[20:21]
	v_pk_mul_f32 v[22:23], v[46:47], v[0:1] op_sel_hi:[1,0]
	v_cvt_pk_bf16_f32 v91, v20, v21
	v_pk_mul_f32 v[4:5], v[218:219], v[22:23]
	v_pk_mul_f32 v[8:9], v[56:57], v[0:1] op_sel_hi:[1,0]
	v_cvt_pk_bf16_f32 v93, v4, v5
	s_waitcnt vmcnt(8)
	v_pk_mul_f32 v[8:9], v[228:229], v[8:9]
	v_pk_mul_f32 v[20:21], v[58:59], v[0:1] op_sel_hi:[1,0]
	v_cvt_pk_bf16_f32 v94, v8, v9
	v_pk_mul_f32 v[2:3], v[224:225], v[20:21]
	v_pk_mul_f32 v[20:21], v[52:53], v[0:1] op_sel_hi:[1,0]
	v_cvt_pk_bf16_f32 v96, v2, v3
	v_pk_mul_f32 v[20:21], v[230:231], v[20:21]
	v_pk_mul_f32 v[22:23], v[54:55], v[0:1] op_sel_hi:[1,0]
	v_cvt_pk_bf16_f32 v95, v20, v21
	v_pk_mul_f32 v[4:5], v[226:227], v[22:23]
	v_pk_mul_f32 v[8:9], v[64:65], v[0:1] op_sel_hi:[1,0]
	v_cvt_pk_bf16_f32 v97, v4, v5
	s_waitcnt vmcnt(6)
	v_pk_mul_f32 v[8:9], v[236:237], v[8:9]
	v_pk_mul_f32 v[20:21], v[66:67], v[0:1] op_sel_hi:[1,0]
	v_cvt_pk_bf16_f32 v98, v8, v9
	v_pk_mul_f32 v[2:3], v[232:233], v[20:21]
	v_pk_mul_f32 v[20:21], v[60:61], v[0:1] op_sel_hi:[1,0]
	v_cvt_pk_bf16_f32 v100, v2, v3
	v_pk_mul_f32 v[20:21], v[238:239], v[20:21]
	v_pk_mul_f32 v[22:23], v[62:63], v[0:1] op_sel_hi:[1,0]
	v_cvt_pk_bf16_f32 v99, v20, v21
	v_pk_mul_f32 v[4:5], v[234:235], v[22:23]
	v_pk_mul_f32 v[8:9], v[72:73], v[0:1] op_sel_hi:[1,0]
	v_cvt_pk_bf16_f32 v101, v4, v5
	s_waitcnt vmcnt(4)
	v_pk_mul_f32 v[8:9], v[244:245], v[8:9]
	v_pk_mul_f32 v[20:21], v[74:75], v[0:1] op_sel_hi:[1,0]
	v_cvt_pk_bf16_f32 v102, v8, v9
	v_pk_mul_f32 v[2:3], v[20:21], v[240:241]
	v_pk_mul_f32 v[20:21], v[68:69], v[0:1] op_sel_hi:[1,0]
	v_cvt_pk_bf16_f32 v104, v2, v3
	v_pk_mul_f32 v[20:21], v[246:247], v[20:21]
	v_pk_mul_f32 v[22:23], v[70:71], v[0:1] op_sel_hi:[1,0]
	v_cvt_pk_bf16_f32 v103, v20, v21
	v_pk_mul_f32 v[4:5], v[22:23], v[242:243]
	v_pk_mul_f32 v[8:9], v[106:107], v[0:1] op_sel_hi:[1,0]
	v_cvt_pk_bf16_f32 v105, v4, v5
	s_waitcnt vmcnt(2)
	v_pk_mul_f32 v[8:9], v[8:9], v[160:161]
	v_pk_mul_f32 v[20:21], v[108:109], v[0:1] op_sel_hi:[1,0]
	v_cvt_pk_bf16_f32 v106, v8, v9
	v_pk_mul_f32 v[2:3], v[20:21], v[156:157]
	v_pk_mul_f32 v[20:21], v[78:79], v[0:1] op_sel_hi:[1,0]
	v_cvt_pk_bf16_f32 v108, v2, v3
	v_pk_mul_f32 v[20:21], v[20:21], v[162:163]
	v_pk_mul_f32 v[22:23], v[80:81], v[0:1] op_sel_hi:[1,0]
	v_cvt_pk_bf16_f32 v107, v20, v21
	v_pk_mul_f32 v[4:5], v[22:23], v[158:159]
	s_nop 0
	v_cvt_pk_bf16_f32 v109, v4, v5
	s_nop 0
	s_waitcnt vmcnt(0)
	v_pk_mul_f32 v[4:5], v[10:11], v[166:167]
	v_pk_mul_f32 v[6:7], v[14:15], v[168:169]
	v_pk_mul_f32 v[14:15], v[16:17], v[0:1] op_sel_hi:[1,0]
	v_pk_mul_f32 v[8:9], v[12:13], v[170:171]
	v_pk_mul_f32 v[2:3], v[14:15], v[164:165]
	v_cvt_pk_bf16_f32 v110, v6, v7
	v_cvt_pk_bf16_f32 v111, v8, v9
	v_cvt_pk_bf16_f32 v112, v2, v3
	v_cvt_pk_bf16_f32 v113, v4, v5
